# final norm fast path: 8 rows per wave loaded up front with counted waits, XCD-local row mapping (on top of combo)
# baseline (speedup 1.0000x reference)
.LBB0_1486:
	v_readlane_b32 s2, v254, 3
	v_readlane_b32 s3, v254, 4
	s_cmp_lt_i32 s2, 32
	s_cselect_b64 s[0:1], -1, 0
	s_cmp_gt_i32 s3, 31
	s_cselect_b64 s[2:3], -1, 0
	s_and_b64 s[0:1], s[0:1], s[2:3]
	s_andn2_b64 vcc, exec, s[0:1]
	s_cbranch_vccnz .LBB0_1490
	v_readlane_b32 s0, v254, 15
	v_readlane_b32 s1, v254, 16
	s_load_dwordx2 s[2:3], s[0:1], 0x108
	v_readlane_b32 s0, v254, 0
	v_mbcnt_lo_u32_b32 v16, -1, 0
	v_mbcnt_hi_u32_b32 v16, -1, v16
	v_readlane_b32 s1, v254, 44
	s_add_i32 s10, s0, s1
	s_waitcnt lgkmcnt(0)
	s_movk_i32 s4, 0xf8
	s_load_dwordx2 s[0:1], s[2:3], 0x100
	s_waitcnt lgkmcnt(0)
	s_load_dwordx2 s[2:3], s[2:3], s4
	s_waitcnt lgkmcnt(0)
	s_cmpk_lt_i32 s10, 0x4000
	s_cbranch_scc0 .LBB0_1490
	v_lshlrev_b32_e32 v0, 2, v16
	v_ashrrev_i32_e32 v1, 31, v0
	s_ashr_i32 s11, s10, 31
	v_lshl_add_u64 v[18:19], v[0:1], 2, s[2:3]
	s_lshl_b64 s[2:3], s[10:11], 12
	s_add_u32 s2, s0, s2
	v_ashrrev_i32_e32 v17, 31, v16
	s_addc_u32 s3, s1, s3
	v_lshlrev_b64 v[34:35], 4, v[16:17]
	v_lshl_add_u64 v[32:33], s[2:3], 0, v[34:35]
	global_load_dwordx4 v[0:3], v[18:19], off
	global_load_dwordx4 v[4:7], v[18:19], off offset:1024
	global_load_dwordx4 v[8:11], v[18:19], off offset:2048
	global_load_dwordx4 v[12:15], v[18:19], off offset:3072
	s_nop 0
	global_load_dwordx4 v[16:19], v[32:33], off offset:3072
	global_load_dwordx4 v[20:23], v[32:33], off offset:2048
	global_load_dwordx4 v[24:27], v[32:33], off offset:1024
	global_load_dwordx4 v[28:31], v[32:33], off
	s_mov_b64 s[2:3], 0x800
	v_lshl_add_u64 v[32:33], v[32:33], 0, s[2:3]
	v_lshl_add_u64 v[34:35], s[0:1], 0, v[34:35]
	s_lshl_b64 s[0:1], s[10:11], 2
	v_readlane_b32 s2, v254, 12
	v_readlane_b32 s3, v254, 13
	s_add_u32 s0, s2, s0
	s_addc_u32 s1, s3, s1
	v_readlane_b32 s14, v255, 4
	s_add_u32 s4, s0, 0x17980000
	v_readlane_b32 s15, v255, 5
	s_addc_u32 s5, s1, 0
	s_ashr_i32 s15, s14, 31
	s_lshl_b64 s[6:7], s[14:15], 2
	s_lshl_b64 s[8:9], s[14:15], 12
	v_mov_b32_e32 v36, 0
	v_mov_b32_e32 v37, 0x358637bd
	s_mov_b32 s11, 0xf800000
	v_mov_b32_e32 v38, 0x260
	s_mul_i32 s12, s14, 7
	s_add_i32 s12, s12, s10
	s_cmpk_lt_i32 s12, 0x4000
	s_cbranch_scc0 .LBB0_1489
	s_add_i32 s12, s12, s14
	s_cmpk_lt_i32 s12, 0x4000
	s_cbranch_scc1 .LBB0_1489
	s_cmpk_eq_i32 s14, 0x800
	s_cbranch_scc0 .LBB0_1489
	s_lshr_b32 s12, s10, 3
	s_and_b32 s13, s12, 7
	s_lshr_b32 s12, s12, 3
	s_lshl_b32 s12, s12, 3
	s_and_b32 s2, s10, 7
	s_add_i32 s12, s12, s2
	s_lshl_b32 s13, s13, 11
	s_add_i32 s12, s12, s13
	s_sub_i32 s2, s12, s10
	s_ashr_i32 s3, s2, 31
	s_lshl_b64 s[16:17], s[2:3], 2
	s_add_u32 s4, s4, s16
	s_addc_u32 s5, s5, s17
	s_lshl_b64 s[16:17], s[2:3], 12
	v_lshl_add_u64 v[32:33], v[32:33], 0, s[16:17]
	s_mov_b32 s10, s12
	s_movk_i32 s14, 0x100
	s_mov_b64 s[6:7], 0x400
	s_mov_b64 s[8:9], 0x100000
	s_ashr_i32 s13, s12, 31
	s_lshl_b64 s[2:3], s[12:13], 12
	v_lshl_add_u64 v[72:73], v[34:35], 0, s[2:3]
	global_load_dwordx4 v[16:19], v[72:73], off offset:3072
	global_load_dwordx4 v[20:23], v[72:73], off offset:2048
	global_load_dwordx4 v[24:27], v[72:73], off offset:1024
	global_load_dwordx4 v[28:31], v[72:73], off
	global_load_dword v192, v36, s[4:5]
	s_mov_b32 s12, s10
	s_add_u32 s4, s4, s6
	s_addc_u32 s5, s5, s7
	s_add_i32 s12, s12, s14
	s_ashr_i32 s13, s12, 31
	s_lshl_b64 s[2:3], s[12:13], 12
	v_lshl_add_u64 v[72:73], v[34:35], 0, s[2:3]
	global_load_dword v193, v36, s[4:5]
	global_load_dwordx4 v[80:83], v[72:73], off offset:3072
	global_load_dwordx4 v[84:87], v[72:73], off offset:2048
	global_load_dwordx4 v[88:91], v[72:73], off offset:1024
	global_load_dwordx4 v[92:95], v[72:73], off
	s_add_u32 s4, s4, s6
	s_addc_u32 s5, s5, s7
	s_add_i32 s12, s12, s14
	s_ashr_i32 s13, s12, 31
	s_lshl_b64 s[2:3], s[12:13], 12
	v_lshl_add_u64 v[72:73], v[34:35], 0, s[2:3]
	global_load_dword v194, v36, s[4:5]
	global_load_dwordx4 v[96:99], v[72:73], off offset:3072
	global_load_dwordx4 v[100:103], v[72:73], off offset:2048
	global_load_dwordx4 v[104:107], v[72:73], off offset:1024
	global_load_dwordx4 v[108:111], v[72:73], off
	s_add_u32 s4, s4, s6
	s_addc_u32 s5, s5, s7
	s_add_i32 s12, s12, s14
	s_ashr_i32 s13, s12, 31
	s_lshl_b64 s[2:3], s[12:13], 12
	v_lshl_add_u64 v[72:73], v[34:35], 0, s[2:3]
	global_load_dword v195, v36, s[4:5]
	global_load_dwordx4 v[112:115], v[72:73], off offset:3072
	global_load_dwordx4 v[116:119], v[72:73], off offset:2048
	global_load_dwordx4 v[120:123], v[72:73], off offset:1024
	global_load_dwordx4 v[124:127], v[72:73], off
	s_add_u32 s4, s4, s6
	s_addc_u32 s5, s5, s7
	s_add_i32 s12, s12, s14
	s_ashr_i32 s13, s12, 31
	s_lshl_b64 s[2:3], s[12:13], 12
	v_lshl_add_u64 v[72:73], v[34:35], 0, s[2:3]
	global_load_dword v196, v36, s[4:5]
	global_load_dwordx4 v[128:131], v[72:73], off offset:3072
	global_load_dwordx4 v[132:135], v[72:73], off offset:2048
	global_load_dwordx4 v[136:139], v[72:73], off offset:1024
	global_load_dwordx4 v[140:143], v[72:73], off
	s_add_u32 s4, s4, s6
	s_addc_u32 s5, s5, s7
	s_add_i32 s12, s12, s14
	s_ashr_i32 s13, s12, 31
	s_lshl_b64 s[2:3], s[12:13], 12
	v_lshl_add_u64 v[72:73], v[34:35], 0, s[2:3]
	global_load_dword v197, v36, s[4:5]
	global_load_dwordx4 v[144:147], v[72:73], off offset:3072
	global_load_dwordx4 v[148:151], v[72:73], off offset:2048
	global_load_dwordx4 v[152:155], v[72:73], off offset:1024
	global_load_dwordx4 v[156:159], v[72:73], off
	s_add_u32 s4, s4, s6
	s_addc_u32 s5, s5, s7
	s_add_i32 s12, s12, s14
	s_ashr_i32 s13, s12, 31
	s_lshl_b64 s[2:3], s[12:13], 12
	v_lshl_add_u64 v[72:73], v[34:35], 0, s[2:3]
	global_load_dword v198, v36, s[4:5]
	global_load_dwordx4 v[160:163], v[72:73], off offset:3072
	global_load_dwordx4 v[164:167], v[72:73], off offset:2048
	global_load_dwordx4 v[168:171], v[72:73], off offset:1024
	global_load_dwordx4 v[172:175], v[72:73], off
	s_add_u32 s4, s4, s6
	s_addc_u32 s5, s5, s7
	s_add_i32 s12, s12, s14
	s_ashr_i32 s13, s12, 31
	s_lshl_b64 s[2:3], s[12:13], 12
	v_lshl_add_u64 v[72:73], v[34:35], 0, s[2:3]
	global_load_dword v199, v36, s[4:5]
	global_load_dwordx4 v[176:179], v[72:73], off offset:3072
	global_load_dwordx4 v[180:183], v[72:73], off offset:2048
	global_load_dwordx4 v[184:187], v[72:73], off offset:1024
	global_load_dwordx4 v[188:191], v[72:73], off
	s_waitcnt vmcnt(35)
	v_fmamk_f32 v192, v192, 0x3a800000, v37
	v_mul_f32_e32 v56, 0x4f800000, v192
	v_cmp_gt_f32_e32 vcc, s11, v192
	s_nop 1
	v_cndmask_b32_e32 v192, v192, v56, vcc
	v_sqrt_f32_e32 v56, v192
	s_nop 0
	v_add_u32_e32 v57, -1, v56
	v_add_u32_e32 v58, 1, v56
	v_fma_f32 v59, -v57, v56, v192
	v_fma_f32 v60, -v58, v56, v192
	v_cmp_ge_f32_e64 s[2:3], 0, v59
	s_nop 1
	v_cndmask_b32_e64 v56, v56, v57, s[2:3]
	v_cmp_lt_f32_e64 s[2:3], 0, v60
	s_nop 1
	v_cndmask_b32_e64 v56, v56, v58, s[2:3]
	v_mul_f32_e32 v57, 0x37800000, v56
	v_cndmask_b32_e32 v56, v56, v57, vcc
	v_cmp_class_f32_e32 vcc, v192, v38
	s_nop 1
	v_cndmask_b32_e32 v192, v56, v192, vcc
	v_div_scale_f32 v56, s[2:3], v192, v192, 1.0
	v_rcp_f32_e32 v58, v56
	v_div_scale_f32 v57, vcc, 1.0, v192, 1.0
	v_fma_f32 v59, -v56, v58, 1.0
	v_fmac_f32_e32 v58, v59, v58
	v_mul_f32_e32 v59, v57, v58
	v_fma_f32 v60, -v56, v59, v57
	v_fmac_f32_e32 v59, v60, v58
	v_fma_f32 v56, -v56, v59, v57
	v_div_fmas_f32 v56, v56, v58, v59
	v_div_fixup_f32 v56, v56, v192, 1.0
	v_pk_mul_f32 v[58:59], v[56:57], v[28:29] op_sel_hi:[0,1]
	v_pk_mul_f32 v[60:61], v[56:57], v[30:31] op_sel_hi:[0,1]
	v_pk_mul_f32 v[62:63], v[56:57], v[24:25] op_sel_hi:[0,1]
	v_pk_mul_f32 v[64:65], v[56:57], v[26:27] op_sel_hi:[0,1]
	v_pk_mul_f32 v[66:67], v[56:57], v[20:21] op_sel_hi:[0,1]
	v_pk_mul_f32 v[68:69], v[56:57], v[22:23] op_sel_hi:[0,1]
	v_pk_mul_f32 v[70:71], v[56:57], v[16:17] op_sel_hi:[0,1]
	v_pk_mul_f32 v[56:57], v[56:57], v[18:19] op_sel_hi:[0,1]
	v_pk_mul_f32 v[42:43], v[60:61], v[2:3]
	v_pk_mul_f32 v[40:41], v[58:59], v[0:1]
	v_pk_mul_f32 v[46:47], v[64:65], v[6:7]
	v_pk_mul_f32 v[44:45], v[62:63], v[4:5]
	v_pk_mul_f32 v[50:51], v[68:69], v[10:11]
	v_pk_mul_f32 v[48:49], v[66:67], v[8:9]
	v_pk_mul_f32 v[54:55], v[56:57], v[14:15]
	v_pk_mul_f32 v[52:53], v[70:71], v[12:13]
	global_store_dwordx4 v[32:33], v[40:43], off offset:-2048
	global_store_dwordx4 v[32:33], v[44:47], off offset:-1024
	global_store_dwordx4 v[32:33], v[48:51], off
	global_store_dwordx4 v[32:33], v[52:55], off offset:1024
	v_lshl_add_u64 v[32:33], v[32:33], 0, s[8:9]
	s_waitcnt vmcnt(34)
	v_fmamk_f32 v193, v193, 0x3a800000, v37
	v_mul_f32_e32 v56, 0x4f800000, v193
	v_cmp_gt_f32_e32 vcc, s11, v193
	s_nop 1
	v_cndmask_b32_e32 v193, v193, v56, vcc
	v_sqrt_f32_e32 v56, v193
	s_nop 0
	v_add_u32_e32 v57, -1, v56
	v_add_u32_e32 v58, 1, v56
	v_fma_f32 v59, -v57, v56, v193
	v_fma_f32 v60, -v58, v56, v193
	v_cmp_ge_f32_e64 s[2:3], 0, v59
	s_nop 1
	v_cndmask_b32_e64 v56, v56, v57, s[2:3]
	v_cmp_lt_f32_e64 s[2:3], 0, v60
	s_nop 1
	v_cndmask_b32_e64 v56, v56, v58, s[2:3]
	v_mul_f32_e32 v57, 0x37800000, v56
	v_cndmask_b32_e32 v56, v56, v57, vcc
	v_cmp_class_f32_e32 vcc, v193, v38
	s_nop 1
	v_cndmask_b32_e32 v193, v56, v193, vcc
	v_div_scale_f32 v56, s[2:3], v193, v193, 1.0
	v_rcp_f32_e32 v58, v56
	v_div_scale_f32 v57, vcc, 1.0, v193, 1.0
	v_fma_f32 v59, -v56, v58, 1.0
	v_fmac_f32_e32 v58, v59, v58
	v_mul_f32_e32 v59, v57, v58
	v_fma_f32 v60, -v56, v59, v57
	v_fmac_f32_e32 v59, v60, v58
	v_fma_f32 v56, -v56, v59, v57
	v_div_fmas_f32 v56, v56, v58, v59
	v_div_fixup_f32 v56, v56, v193, 1.0
	v_pk_mul_f32 v[58:59], v[56:57], v[92:93] op_sel_hi:[0,1]
	v_pk_mul_f32 v[60:61], v[56:57], v[94:95] op_sel_hi:[0,1]
	v_pk_mul_f32 v[62:63], v[56:57], v[88:89] op_sel_hi:[0,1]
	v_pk_mul_f32 v[64:65], v[56:57], v[90:91] op_sel_hi:[0,1]
	v_pk_mul_f32 v[66:67], v[56:57], v[84:85] op_sel_hi:[0,1]
	v_pk_mul_f32 v[68:69], v[56:57], v[86:87] op_sel_hi:[0,1]
	v_pk_mul_f32 v[70:71], v[56:57], v[80:81] op_sel_hi:[0,1]
	v_pk_mul_f32 v[56:57], v[56:57], v[82:83] op_sel_hi:[0,1]
	v_pk_mul_f32 v[42:43], v[60:61], v[2:3]
	v_pk_mul_f32 v[40:41], v[58:59], v[0:1]
	v_pk_mul_f32 v[46:47], v[64:65], v[6:7]
	v_pk_mul_f32 v[44:45], v[62:63], v[4:5]
	v_pk_mul_f32 v[50:51], v[68:69], v[10:11]
	v_pk_mul_f32 v[48:49], v[66:67], v[8:9]
	v_pk_mul_f32 v[54:55], v[56:57], v[14:15]
	v_pk_mul_f32 v[52:53], v[70:71], v[12:13]
	global_store_dwordx4 v[32:33], v[40:43], off offset:-2048
	global_store_dwordx4 v[32:33], v[44:47], off offset:-1024
	global_store_dwordx4 v[32:33], v[48:51], off
	global_store_dwordx4 v[32:33], v[52:55], off offset:1024
	v_lshl_add_u64 v[32:33], v[32:33], 0, s[8:9]
	s_waitcnt vmcnt(33)
	v_fmamk_f32 v194, v194, 0x3a800000, v37
	v_mul_f32_e32 v56, 0x4f800000, v194
	v_cmp_gt_f32_e32 vcc, s11, v194
	s_nop 1
	v_cndmask_b32_e32 v194, v194, v56, vcc
	v_sqrt_f32_e32 v56, v194
	s_nop 0
	v_add_u32_e32 v57, -1, v56
	v_add_u32_e32 v58, 1, v56
	v_fma_f32 v59, -v57, v56, v194
	v_fma_f32 v60, -v58, v56, v194
	v_cmp_ge_f32_e64 s[2:3], 0, v59
	s_nop 1
	v_cndmask_b32_e64 v56, v56, v57, s[2:3]
	v_cmp_lt_f32_e64 s[2:3], 0, v60
	s_nop 1
	v_cndmask_b32_e64 v56, v56, v58, s[2:3]
	v_mul_f32_e32 v57, 0x37800000, v56
	v_cndmask_b32_e32 v56, v56, v57, vcc
	v_cmp_class_f32_e32 vcc, v194, v38
	s_nop 1
	v_cndmask_b32_e32 v194, v56, v194, vcc
	v_div_scale_f32 v56, s[2:3], v194, v194, 1.0
	v_rcp_f32_e32 v58, v56
	v_div_scale_f32 v57, vcc, 1.0, v194, 1.0
	v_fma_f32 v59, -v56, v58, 1.0
	v_fmac_f32_e32 v58, v59, v58
	v_mul_f32_e32 v59, v57, v58
	v_fma_f32 v60, -v56, v59, v57
	v_fmac_f32_e32 v59, v60, v58
	v_fma_f32 v56, -v56, v59, v57
	v_div_fmas_f32 v56, v56, v58, v59
	v_div_fixup_f32 v56, v56, v194, 1.0
	v_pk_mul_f32 v[58:59], v[56:57], v[108:109] op_sel_hi:[0,1]
	v_pk_mul_f32 v[60:61], v[56:57], v[110:111] op_sel_hi:[0,1]
	v_pk_mul_f32 v[62:63], v[56:57], v[104:105] op_sel_hi:[0,1]
	v_pk_mul_f32 v[64:65], v[56:57], v[106:107] op_sel_hi:[0,1]
	v_pk_mul_f32 v[66:67], v[56:57], v[100:101] op_sel_hi:[0,1]
	v_pk_mul_f32 v[68:69], v[56:57], v[102:103] op_sel_hi:[0,1]
	v_pk_mul_f32 v[70:71], v[56:57], v[96:97] op_sel_hi:[0,1]
	v_pk_mul_f32 v[56:57], v[56:57], v[98:99] op_sel_hi:[0,1]
	v_pk_mul_f32 v[42:43], v[60:61], v[2:3]
	v_pk_mul_f32 v[40:41], v[58:59], v[0:1]
	v_pk_mul_f32 v[46:47], v[64:65], v[6:7]
	v_pk_mul_f32 v[44:45], v[62:63], v[4:5]
	v_pk_mul_f32 v[50:51], v[68:69], v[10:11]
	v_pk_mul_f32 v[48:49], v[66:67], v[8:9]
	v_pk_mul_f32 v[54:55], v[56:57], v[14:15]
	v_pk_mul_f32 v[52:53], v[70:71], v[12:13]
	global_store_dwordx4 v[32:33], v[40:43], off offset:-2048
	global_store_dwordx4 v[32:33], v[44:47], off offset:-1024
	global_store_dwordx4 v[32:33], v[48:51], off
	global_store_dwordx4 v[32:33], v[52:55], off offset:1024
	v_lshl_add_u64 v[32:33], v[32:33], 0, s[8:9]
	s_waitcnt vmcnt(32)
	v_fmamk_f32 v195, v195, 0x3a800000, v37
	v_mul_f32_e32 v56, 0x4f800000, v195
	v_cmp_gt_f32_e32 vcc, s11, v195
	s_nop 1
	v_cndmask_b32_e32 v195, v195, v56, vcc
	v_sqrt_f32_e32 v56, v195
	s_nop 0
	v_add_u32_e32 v57, -1, v56
	v_add_u32_e32 v58, 1, v56
	v_fma_f32 v59, -v57, v56, v195
	v_fma_f32 v60, -v58, v56, v195
	v_cmp_ge_f32_e64 s[2:3], 0, v59
	s_nop 1
	v_cndmask_b32_e64 v56, v56, v57, s[2:3]
	v_cmp_lt_f32_e64 s[2:3], 0, v60
	s_nop 1
	v_cndmask_b32_e64 v56, v56, v58, s[2:3]
	v_mul_f32_e32 v57, 0x37800000, v56
	v_cndmask_b32_e32 v56, v56, v57, vcc
	v_cmp_class_f32_e32 vcc, v195, v38
	s_nop 1
	v_cndmask_b32_e32 v195, v56, v195, vcc
	v_div_scale_f32 v56, s[2:3], v195, v195, 1.0
	v_rcp_f32_e32 v58, v56
	v_div_scale_f32 v57, vcc, 1.0, v195, 1.0
	v_fma_f32 v59, -v56, v58, 1.0
	v_fmac_f32_e32 v58, v59, v58
	v_mul_f32_e32 v59, v57, v58
	v_fma_f32 v60, -v56, v59, v57
	v_fmac_f32_e32 v59, v60, v58
	v_fma_f32 v56, -v56, v59, v57
	v_div_fmas_f32 v56, v56, v58, v59
	v_div_fixup_f32 v56, v56, v195, 1.0
	v_pk_mul_f32 v[58:59], v[56:57], v[124:125] op_sel_hi:[0,1]
	v_pk_mul_f32 v[60:61], v[56:57], v[126:127] op_sel_hi:[0,1]
	v_pk_mul_f32 v[62:63], v[56:57], v[120:121] op_sel_hi:[0,1]
	v_pk_mul_f32 v[64:65], v[56:57], v[122:123] op_sel_hi:[0,1]
	v_pk_mul_f32 v[66:67], v[56:57], v[116:117] op_sel_hi:[0,1]
	v_pk_mul_f32 v[68:69], v[56:57], v[118:119] op_sel_hi:[0,1]
	v_pk_mul_f32 v[70:71], v[56:57], v[112:113] op_sel_hi:[0,1]
	v_pk_mul_f32 v[56:57], v[56:57], v[114:115] op_sel_hi:[0,1]
	v_pk_mul_f32 v[42:43], v[60:61], v[2:3]
	v_pk_mul_f32 v[40:41], v[58:59], v[0:1]
	v_pk_mul_f32 v[46:47], v[64:65], v[6:7]
	v_pk_mul_f32 v[44:45], v[62:63], v[4:5]
	v_pk_mul_f32 v[50:51], v[68:69], v[10:11]
	v_pk_mul_f32 v[48:49], v[66:67], v[8:9]
	v_pk_mul_f32 v[54:55], v[56:57], v[14:15]
	v_pk_mul_f32 v[52:53], v[70:71], v[12:13]
	global_store_dwordx4 v[32:33], v[40:43], off offset:-2048
	global_store_dwordx4 v[32:33], v[44:47], off offset:-1024
	global_store_dwordx4 v[32:33], v[48:51], off
	global_store_dwordx4 v[32:33], v[52:55], off offset:1024
	v_lshl_add_u64 v[32:33], v[32:33], 0, s[8:9]
	s_waitcnt vmcnt(31)
	v_fmamk_f32 v196, v196, 0x3a800000, v37
	v_mul_f32_e32 v56, 0x4f800000, v196
	v_cmp_gt_f32_e32 vcc, s11, v196
	s_nop 1
	v_cndmask_b32_e32 v196, v196, v56, vcc
	v_sqrt_f32_e32 v56, v196
	s_nop 0
	v_add_u32_e32 v57, -1, v56
	v_add_u32_e32 v58, 1, v56
	v_fma_f32 v59, -v57, v56, v196
	v_fma_f32 v60, -v58, v56, v196
	v_cmp_ge_f32_e64 s[2:3], 0, v59
	s_nop 1
	v_cndmask_b32_e64 v56, v56, v57, s[2:3]
	v_cmp_lt_f32_e64 s[2:3], 0, v60
	s_nop 1
	v_cndmask_b32_e64 v56, v56, v58, s[2:3]
	v_mul_f32_e32 v57, 0x37800000, v56
	v_cndmask_b32_e32 v56, v56, v57, vcc
	v_cmp_class_f32_e32 vcc, v196, v38
	s_nop 1
	v_cndmask_b32_e32 v196, v56, v196, vcc
	v_div_scale_f32 v56, s[2:3], v196, v196, 1.0
	v_rcp_f32_e32 v58, v56
	v_div_scale_f32 v57, vcc, 1.0, v196, 1.0
	v_fma_f32 v59, -v56, v58, 1.0
	v_fmac_f32_e32 v58, v59, v58
	v_mul_f32_e32 v59, v57, v58
	v_fma_f32 v60, -v56, v59, v57
	v_fmac_f32_e32 v59, v60, v58
	v_fma_f32 v56, -v56, v59, v57
	v_div_fmas_f32 v56, v56, v58, v59
	v_div_fixup_f32 v56, v56, v196, 1.0
	v_pk_mul_f32 v[58:59], v[56:57], v[140:141] op_sel_hi:[0,1]
	v_pk_mul_f32 v[60:61], v[56:57], v[142:143] op_sel_hi:[0,1]
	v_pk_mul_f32 v[62:63], v[56:57], v[136:137] op_sel_hi:[0,1]
	v_pk_mul_f32 v[64:65], v[56:57], v[138:139] op_sel_hi:[0,1]
	v_pk_mul_f32 v[66:67], v[56:57], v[132:133] op_sel_hi:[0,1]
	v_pk_mul_f32 v[68:69], v[56:57], v[134:135] op_sel_hi:[0,1]
	v_pk_mul_f32 v[70:71], v[56:57], v[128:129] op_sel_hi:[0,1]
	v_pk_mul_f32 v[56:57], v[56:57], v[130:131] op_sel_hi:[0,1]
	v_pk_mul_f32 v[42:43], v[60:61], v[2:3]
	v_pk_mul_f32 v[40:41], v[58:59], v[0:1]
	v_pk_mul_f32 v[46:47], v[64:65], v[6:7]
	v_pk_mul_f32 v[44:45], v[62:63], v[4:5]
	v_pk_mul_f32 v[50:51], v[68:69], v[10:11]
	v_pk_mul_f32 v[48:49], v[66:67], v[8:9]
	v_pk_mul_f32 v[54:55], v[56:57], v[14:15]
	v_pk_mul_f32 v[52:53], v[70:71], v[12:13]
	global_store_dwordx4 v[32:33], v[40:43], off offset:-2048
	global_store_dwordx4 v[32:33], v[44:47], off offset:-1024
	global_store_dwordx4 v[32:33], v[48:51], off
	global_store_dwordx4 v[32:33], v[52:55], off offset:1024
	v_lshl_add_u64 v[32:33], v[32:33], 0, s[8:9]
	s_waitcnt vmcnt(30)
	v_fmamk_f32 v197, v197, 0x3a800000, v37
	v_mul_f32_e32 v56, 0x4f800000, v197
	v_cmp_gt_f32_e32 vcc, s11, v197
	s_nop 1
	v_cndmask_b32_e32 v197, v197, v56, vcc
	v_sqrt_f32_e32 v56, v197
	s_nop 0
	v_add_u32_e32 v57, -1, v56
	v_add_u32_e32 v58, 1, v56
	v_fma_f32 v59, -v57, v56, v197
	v_fma_f32 v60, -v58, v56, v197
	v_cmp_ge_f32_e64 s[2:3], 0, v59
	s_nop 1
	v_cndmask_b32_e64 v56, v56, v57, s[2:3]
	v_cmp_lt_f32_e64 s[2:3], 0, v60
	s_nop 1
	v_cndmask_b32_e64 v56, v56, v58, s[2:3]
	v_mul_f32_e32 v57, 0x37800000, v56
	v_cndmask_b32_e32 v56, v56, v57, vcc
	v_cmp_class_f32_e32 vcc, v197, v38
	s_nop 1
	v_cndmask_b32_e32 v197, v56, v197, vcc
	v_div_scale_f32 v56, s[2:3], v197, v197, 1.0
	v_rcp_f32_e32 v58, v56
	v_div_scale_f32 v57, vcc, 1.0, v197, 1.0
	v_fma_f32 v59, -v56, v58, 1.0
	v_fmac_f32_e32 v58, v59, v58
	v_mul_f32_e32 v59, v57, v58
	v_fma_f32 v60, -v56, v59, v57
	v_fmac_f32_e32 v59, v60, v58
	v_fma_f32 v56, -v56, v59, v57
	v_div_fmas_f32 v56, v56, v58, v59
	v_div_fixup_f32 v56, v56, v197, 1.0
	v_pk_mul_f32 v[58:59], v[56:57], v[156:157] op_sel_hi:[0,1]
	v_pk_mul_f32 v[60:61], v[56:57], v[158:159] op_sel_hi:[0,1]
	v_pk_mul_f32 v[62:63], v[56:57], v[152:153] op_sel_hi:[0,1]
	v_pk_mul_f32 v[64:65], v[56:57], v[154:155] op_sel_hi:[0,1]
	v_pk_mul_f32 v[66:67], v[56:57], v[148:149] op_sel_hi:[0,1]
	v_pk_mul_f32 v[68:69], v[56:57], v[150:151] op_sel_hi:[0,1]
	v_pk_mul_f32 v[70:71], v[56:57], v[144:145] op_sel_hi:[0,1]
	v_pk_mul_f32 v[56:57], v[56:57], v[146:147] op_sel_hi:[0,1]
	v_pk_mul_f32 v[42:43], v[60:61], v[2:3]
	v_pk_mul_f32 v[40:41], v[58:59], v[0:1]
	v_pk_mul_f32 v[46:47], v[64:65], v[6:7]
	v_pk_mul_f32 v[44:45], v[62:63], v[4:5]
	v_pk_mul_f32 v[50:51], v[68:69], v[10:11]
	v_pk_mul_f32 v[48:49], v[66:67], v[8:9]
	v_pk_mul_f32 v[54:55], v[56:57], v[14:15]
	v_pk_mul_f32 v[52:53], v[70:71], v[12:13]
	global_store_dwordx4 v[32:33], v[40:43], off offset:-2048
	global_store_dwordx4 v[32:33], v[44:47], off offset:-1024
	global_store_dwordx4 v[32:33], v[48:51], off
	global_store_dwordx4 v[32:33], v[52:55], off offset:1024
	v_lshl_add_u64 v[32:33], v[32:33], 0, s[8:9]
	s_waitcnt vmcnt(29)
	v_fmamk_f32 v198, v198, 0x3a800000, v37
	v_mul_f32_e32 v56, 0x4f800000, v198
	v_cmp_gt_f32_e32 vcc, s11, v198
	s_nop 1
	v_cndmask_b32_e32 v198, v198, v56, vcc
	v_sqrt_f32_e32 v56, v198
	s_nop 0
	v_add_u32_e32 v57, -1, v56
	v_add_u32_e32 v58, 1, v56
	v_fma_f32 v59, -v57, v56, v198
	v_fma_f32 v60, -v58, v56, v198
	v_cmp_ge_f32_e64 s[2:3], 0, v59
	s_nop 1
	v_cndmask_b32_e64 v56, v56, v57, s[2:3]
	v_cmp_lt_f32_e64 s[2:3], 0, v60
	s_nop 1
	v_cndmask_b32_e64 v56, v56, v58, s[2:3]
	v_mul_f32_e32 v57, 0x37800000, v56
	v_cndmask_b32_e32 v56, v56, v57, vcc
	v_cmp_class_f32_e32 vcc, v198, v38
	s_nop 1
	v_cndmask_b32_e32 v198, v56, v198, vcc
	v_div_scale_f32 v56, s[2:3], v198, v198, 1.0
	v_rcp_f32_e32 v58, v56
	v_div_scale_f32 v57, vcc, 1.0, v198, 1.0
	v_fma_f32 v59, -v56, v58, 1.0
	v_fmac_f32_e32 v58, v59, v58
	v_mul_f32_e32 v59, v57, v58
	v_fma_f32 v60, -v56, v59, v57
	v_fmac_f32_e32 v59, v60, v58
	v_fma_f32 v56, -v56, v59, v57
	v_div_fmas_f32 v56, v56, v58, v59
	v_div_fixup_f32 v56, v56, v198, 1.0
	v_pk_mul_f32 v[58:59], v[56:57], v[172:173] op_sel_hi:[0,1]
	v_pk_mul_f32 v[60:61], v[56:57], v[174:175] op_sel_hi:[0,1]
	v_pk_mul_f32 v[62:63], v[56:57], v[168:169] op_sel_hi:[0,1]
	v_pk_mul_f32 v[64:65], v[56:57], v[170:171] op_sel_hi:[0,1]
	v_pk_mul_f32 v[66:67], v[56:57], v[164:165] op_sel_hi:[0,1]
	v_pk_mul_f32 v[68:69], v[56:57], v[166:167] op_sel_hi:[0,1]
	v_pk_mul_f32 v[70:71], v[56:57], v[160:161] op_sel_hi:[0,1]
	v_pk_mul_f32 v[56:57], v[56:57], v[162:163] op_sel_hi:[0,1]
	v_pk_mul_f32 v[42:43], v[60:61], v[2:3]
	v_pk_mul_f32 v[40:41], v[58:59], v[0:1]
	v_pk_mul_f32 v[46:47], v[64:65], v[6:7]
	v_pk_mul_f32 v[44:45], v[62:63], v[4:5]
	v_pk_mul_f32 v[50:51], v[68:69], v[10:11]
	v_pk_mul_f32 v[48:49], v[66:67], v[8:9]
	v_pk_mul_f32 v[54:55], v[56:57], v[14:15]
	v_pk_mul_f32 v[52:53], v[70:71], v[12:13]
	global_store_dwordx4 v[32:33], v[40:43], off offset:-2048
	global_store_dwordx4 v[32:33], v[44:47], off offset:-1024
	global_store_dwordx4 v[32:33], v[48:51], off
	global_store_dwordx4 v[32:33], v[52:55], off offset:1024
	v_lshl_add_u64 v[32:33], v[32:33], 0, s[8:9]
	s_waitcnt vmcnt(28)
	v_fmamk_f32 v199, v199, 0x3a800000, v37
	v_mul_f32_e32 v56, 0x4f800000, v199
	v_cmp_gt_f32_e32 vcc, s11, v199
	s_nop 1
	v_cndmask_b32_e32 v199, v199, v56, vcc
	v_sqrt_f32_e32 v56, v199
	s_nop 0
	v_add_u32_e32 v57, -1, v56
	v_add_u32_e32 v58, 1, v56
	v_fma_f32 v59, -v57, v56, v199
	v_fma_f32 v60, -v58, v56, v199
	v_cmp_ge_f32_e64 s[2:3], 0, v59
	s_nop 1
	v_cndmask_b32_e64 v56, v56, v57, s[2:3]
	v_cmp_lt_f32_e64 s[2:3], 0, v60
	s_nop 1
	v_cndmask_b32_e64 v56, v56, v58, s[2:3]
	v_mul_f32_e32 v57, 0x37800000, v56
	v_cndmask_b32_e32 v56, v56, v57, vcc
	v_cmp_class_f32_e32 vcc, v199, v38
	s_nop 1
	v_cndmask_b32_e32 v199, v56, v199, vcc
	v_div_scale_f32 v56, s[2:3], v199, v199, 1.0
	v_rcp_f32_e32 v58, v56
	v_div_scale_f32 v57, vcc, 1.0, v199, 1.0
	v_fma_f32 v59, -v56, v58, 1.0
	v_fmac_f32_e32 v58, v59, v58
	v_mul_f32_e32 v59, v57, v58
	v_fma_f32 v60, -v56, v59, v57
	v_fmac_f32_e32 v59, v60, v58
	v_fma_f32 v56, -v56, v59, v57
	v_div_fmas_f32 v56, v56, v58, v59
	v_div_fixup_f32 v56, v56, v199, 1.0
	v_pk_mul_f32 v[58:59], v[56:57], v[188:189] op_sel_hi:[0,1]
	v_pk_mul_f32 v[60:61], v[56:57], v[190:191] op_sel_hi:[0,1]
	v_pk_mul_f32 v[62:63], v[56:57], v[184:185] op_sel_hi:[0,1]
	v_pk_mul_f32 v[64:65], v[56:57], v[186:187] op_sel_hi:[0,1]
	v_pk_mul_f32 v[66:67], v[56:57], v[180:181] op_sel_hi:[0,1]
	v_pk_mul_f32 v[68:69], v[56:57], v[182:183] op_sel_hi:[0,1]
	v_pk_mul_f32 v[70:71], v[56:57], v[176:177] op_sel_hi:[0,1]
	v_pk_mul_f32 v[56:57], v[56:57], v[178:179] op_sel_hi:[0,1]
	v_pk_mul_f32 v[42:43], v[60:61], v[2:3]
	v_pk_mul_f32 v[40:41], v[58:59], v[0:1]
	v_pk_mul_f32 v[46:47], v[64:65], v[6:7]
	v_pk_mul_f32 v[44:45], v[62:63], v[4:5]
	v_pk_mul_f32 v[50:51], v[68:69], v[10:11]
	v_pk_mul_f32 v[48:49], v[66:67], v[8:9]
	v_pk_mul_f32 v[54:55], v[56:57], v[14:15]
	v_pk_mul_f32 v[52:53], v[70:71], v[12:13]
	global_store_dwordx4 v[32:33], v[40:43], off offset:-2048
	global_store_dwordx4 v[32:33], v[44:47], off offset:-1024
	global_store_dwordx4 v[32:33], v[48:51], off
	global_store_dwordx4 v[32:33], v[52:55], off offset:1024
	s_branch .LBB0_1490
